# row phase: residual-stream X stores made write-through (sc1) to cut the L2 write-back at the grid barrier
# speedup vs baseline: 1.0039x; 1.0039x over previous
.LBB0_484:
	v_lshlrev_b64 v[138:139], 12, v[128:129]
	v_lshl_add_u64 v[138:139], v[104:105], 0, v[138:139]
	s_and_b64 vcc, exec, s[6:7]
	s_waitcnt vmcnt(3)
	global_store_dwordx4 v[138:139], v[94:97], off sc1
	s_waitcnt vmcnt(3)
	global_store_dwordx4 v[138:139], v[90:93], off offset:1024 sc1
	s_waitcnt vmcnt(3)
	global_store_dwordx4 v[138:139], v[86:89], off offset:2048 sc1
	s_waitcnt vmcnt(3)
	global_store_dwordx4 v[138:139], v[82:85], off offset:3072 sc1
	s_cbranch_vccnz .LBB0_469
	v_mov_b32_e32 v138, v90
	v_mov_b32_e32 v139, v94
	v_pk_mul_f32 v[138:139], v[138:139], v[138:139]
	v_mov_b32_e32 v140, v91
	v_mov_b32_e32 v141, v95
	v_pk_fma_f32 v[138:139], v[140:141], v[140:141], v[138:139]
	v_mov_b32_e32 v140, v92
	v_mov_b32_e32 v141, v96
	v_pk_fma_f32 v[138:139], v[140:141], v[140:141], v[138:139]
	v_mov_b32_e32 v140, v93
	v_mov_b32_e32 v141, v97
	v_pk_fma_f32 v[138:139], v[140:141], v[140:141], v[138:139]
	v_mov_b32_e32 v140, v82
	v_mov_b32_e32 v141, v86
	v_pk_mul_f32 v[140:141], v[140:141], v[140:141]
	v_mov_b32_e32 v142, v83
	v_mov_b32_e32 v143, v87
	v_pk_fma_f32 v[140:141], v[142:143], v[142:143], v[140:141]
	v_mov_b32_e32 v142, v84
	v_mov_b32_e32 v143, v88
	v_pk_fma_f32 v[140:141], v[142:143], v[142:143], v[140:141]
	v_mov_b32_e32 v142, v85
	v_mov_b32_e32 v143, v89
	v_add_u32_e32 v137, 64, v137
	v_pk_fma_f32 v[140:141], v[142:143], v[142:143], v[140:141]
	v_add_f32_e32 v138, v138, v139
	v_cmp_lt_i32_e32 vcc, v136, v137
	v_add_f32_e32 v138, v141, v138
	v_add_f32_e32 v138, v140, v138
	v_cndmask_b32_e32 v136, v198, v136, vcc
	v_lshlrev_b32_e32 v136, 2, v136
	ds_bpermute_b32 v136, v136, v138
	v_cmp_lt_i32_e32 vcc, v135, v137
	v_lshlrev_b64 v[128:129], 11, v[128:129]
	v_lshl_add_u64 v[128:129], v[106:107], 0, v[128:129]
	v_cndmask_b32_e32 v135, v198, v135, vcc
	s_waitcnt lgkmcnt(0)
	v_add_f32_e32 v136, v138, v136
	v_lshlrev_b32_e32 v135, 2, v135
	ds_bpermute_b32 v135, v135, v136
	v_cmp_lt_i32_e32 vcc, v134, v137
	s_waitcnt lgkmcnt(0)
	v_add_f32_e32 v135, v136, v135
	v_cndmask_b32_e32 v134, v198, v134, vcc
	v_lshlrev_b32_e32 v134, 2, v134
	ds_bpermute_b32 v134, v134, v135
	v_cmp_lt_i32_e32 vcc, v133, v137
	s_waitcnt lgkmcnt(0)
	v_add_f32_e32 v134, v135, v134
	v_cndmask_b32_e32 v133, v198, v133, vcc
	v_lshlrev_b32_e32 v133, 2, v133
	ds_bpermute_b32 v133, v133, v134
	v_cmp_lt_i32_e32 vcc, v132, v137
	s_waitcnt lgkmcnt(0)
	v_add_f32_e32 v133, v134, v133
	v_cndmask_b32_e32 v132, v198, v132, vcc
	v_lshlrev_b32_e32 v132, 2, v132
	ds_bpermute_b32 v132, v132, v133
	v_cmp_lt_i32_e32 vcc, v130, v137
	s_waitcnt lgkmcnt(0)
	v_add_f32_e32 v132, v133, v132
	v_cndmask_b32_e32 v130, v198, v130, vcc
	v_lshlrev_b32_e32 v130, 2, v130
	ds_bpermute_b32 v130, v130, v132
	s_waitcnt lgkmcnt(0)
	v_add_f32_e32 v130, v132, v130
	v_fmamk_f32 v130, v130, 0x3a800000, v197
	v_mul_f32_e32 v132, 0x4b800000, v130
	v_cmp_gt_f32_e32 vcc, s14, v130
	s_nop 1
	v_cndmask_b32_e32 v130, v130, v132, vcc
	v_rsq_f32_e32 v130, v130
	s_nop 0
	v_mul_f32_e32 v132, 0x45800000, v130
	v_cndmask_b32_e32 v130, v130, v132, vcc
	v_pk_mul_f32 v[94:95], v[94:95], v[130:131] op_sel_hi:[1,0]
	v_pk_add_f32 v[132:133], v[6:7], 1.0 op_sel_hi:[1,0]
	v_pk_mul_f32 v[94:95], v[2:3], v[94:95]
	v_pk_mul_f32 v[96:97], v[96:97], v[130:131] op_sel_hi:[1,0]
	v_pk_fma_f32 v[94:95], v[132:133], v[94:95], v[14:15]
	v_pk_add_f32 v[132:133], v[8:9], 1.0 op_sel_hi:[1,0]
	v_pk_mul_f32 v[96:97], v[4:5], v[96:97]
	v_cvt_pk_bf16_f32 v94, v94, v95
	v_pk_fma_f32 v[96:97], v[132:133], v[96:97], v[16:17]
	v_pk_mul_f32 v[90:91], v[90:91], v[130:131] op_sel_hi:[1,0]
	v_cvt_pk_bf16_f32 v95, v96, v97
	global_store_dwordx2 v[128:129], v[94:95], off
	v_pk_add_f32 v[94:95], v[22:23], 1.0 op_sel_hi:[1,0]
	v_pk_mul_f32 v[90:91], v[18:19], v[90:91]
	v_pk_mul_f32 v[92:93], v[92:93], v[130:131] op_sel_hi:[1,0]
	v_pk_fma_f32 v[90:91], v[94:95], v[90:91], v[30:31]
	v_pk_add_f32 v[94:95], v[24:25], 1.0 op_sel_hi:[1,0]
	v_pk_mul_f32 v[92:93], v[20:21], v[92:93]
	v_cvt_pk_bf16_f32 v90, v90, v91
	v_pk_fma_f32 v[92:93], v[94:95], v[92:93], v[32:33]
	v_pk_mul_f32 v[86:87], v[86:87], v[130:131] op_sel_hi:[1,0]
	v_cvt_pk_bf16_f32 v91, v92, v93
	global_store_dwordx2 v[128:129], v[90:91], off offset:512
	v_pk_add_f32 v[90:91], v[46:47], 1.0 op_sel_hi:[1,0]
	v_pk_mul_f32 v[86:87], v[34:35], v[86:87]
	v_pk_mul_f32 v[88:89], v[88:89], v[130:131] op_sel_hi:[1,0]
	v_pk_fma_f32 v[86:87], v[90:91], v[86:87], v[50:51]
	v_pk_add_f32 v[90:91], v[48:49], 1.0 op_sel_hi:[1,0]
	v_pk_mul_f32 v[88:89], v[36:37], v[88:89]
	v_cvt_pk_bf16_f32 v86, v86, v87
	v_pk_fma_f32 v[88:89], v[90:91], v[88:89], v[52:53]
	v_pk_mul_f32 v[82:83], v[82:83], v[130:131] op_sel_hi:[1,0]
	v_cvt_pk_bf16_f32 v87, v88, v89
	global_store_dwordx2 v[128:129], v[86:87], off offset:1024
	v_pk_add_f32 v[86:87], v[62:63], 1.0 op_sel_hi:[1,0]
	v_pk_mul_f32 v[82:83], v[58:59], v[82:83]
	v_pk_mul_f32 v[84:85], v[84:85], v[130:131] op_sel_hi:[1,0]
	v_pk_fma_f32 v[82:83], v[86:87], v[82:83], v[70:71]
	v_pk_add_f32 v[86:87], v[64:65], 1.0 op_sel_hi:[1,0]
	v_pk_mul_f32 v[84:85], v[60:61], v[84:85]
	v_cvt_pk_bf16_f32 v82, v82, v83
	v_pk_fma_f32 v[84:85], v[86:87], v[84:85], v[72:73]
	s_nop 0
	v_cvt_pk_bf16_f32 v83, v84, v85
	global_store_dwordx2 v[128:129], v[82:83], off offset:1536
	s_branch .LBB0_469
